# attention units: wait for the 2nd K/V chunk moved from right after the prologue barrier to its first consumer (dead copies skipped)
# speedup vs baseline: 1.0044x; 1.0007x over previous
; #define LAS __attribute__((address_space(3)))
; __device__ __forceinline__ int xcd_vcu() { const int G = gridDim.x, bx = blockIdx.x; return (G % 8 == 0) ? (bx % 8) * (G / 8) + bx / 8 : bx; }
; __device__ __forceinline__ void attn_phase(const Args& a, int o, LAS unsigned char* lds) {
;     ...
;         for (int unit = xcd_vcu(); unit < 4096; unit += gridDim.x) {
;             const int b = unit >> 9, h = (unit >> 5) & 15, c0 = (unit & 31) * 4;
;             const int c = c0 + (wu >> 1), half = wu & 1;
;             const size_t qrow0 = (size_t)b * TPR + c * 64 + half * 32;
;             const int qpos0 = c * 64 + half * 32;
;             const int kc_lo = c0 >= 8 ? c0 - 8 : 0, kc_hi = c0 + 3, my_lo = c >= 8 ? c - 8 : 0;
;             const LAS float* bh = bias + h * 257 + 128;
;             const float bfar = bh[128];
;             bf16x8 qf[2][2];
; #pragma unroll
;             for (int qt = 0; qt < 2; ++qt)
; #pragma unroll
;                 for (int kk = 0; kk < 2; ++kk) qf[qt][kk] = ld_frag(Q + (qrow0 + 16 * qt + i16) * 1024 + h * 64 + 32 * kk + 8 * g);
;             f32x4 ot[4][2];
; #pragma unroll
;             for (int dt = 0; dt < 4; ++dt) { ot[dt][0] = (f32x4){0.f, 0.f, 0.f, 0.f}; ot[dt][1] = (f32x4){0.f, 0.f, 0.f, 0.f}; }
;             float mrun[2] = {-1e30f, -1e30f}, lrun[2] = {0.f, 0.f};
;             const bf16* kg_ = Kb + ((size_t)b * TPR + srow) * 1024 + h * 64 + sseg;
;             const bf16* vg_ = Vt + (size_t)(h * 64 + srow) * LDV + (size_t)b * TPR + sseg;
;             v4u kreg = *(const v4u*)(kg_ + (size_t)(64 * kc_lo) * 1024), vreg = *(const v4u*)(vg_ + 64 * kc_lo);
;             *(LAS v4u*)(KT + srow * KVP + sseg) = kreg; *(LAS v4u*)(VT + srow * KVP + sseg) = vreg;
;             kreg = *(const v4u*)(kg_ + (size_t)(64 * (kc_lo + 1)) * 1024); vreg = *(const v4u*)(vg_ + 64 * (kc_lo + 1));
;             v4u kreg2 = kreg, vreg2 = vreg;
;             __syncthreads();
.LBB0_91:
	s_and_b32 s12, s11, 0x7c
	s_min_u32 s13, s12, 8
	s_add_i32 s15, s3, s13
	s_sub_i32 s12, s12, s13
	s_lshl_b32 s13, s14, 2
	s_lshl_b32 s12, s12, 6
	s_and_b32 s39, s13, 0x7c
	s_or_b32 s38, s12, 0x80
	s_ashr_i32 s12, s14, 9
	s_add_i32 s16, s39, s3
	s_lshl_b32 s15, s15, 6
	s_ashr_i32 s13, s12, 31
	s_lshl_b32 s17, s16, 6
	s_add_i32 s15, s10, s15
	s_bfe_u32 s33, s14, 0x40005
	s_lshl_b64 s[18:19], s[12:13], 13
	s_ashr_i32 s29, s17, 31
	s_add_u32 s28, s18, s17
	s_addc_u32 s29, s19, s29
	s_or_b64 s[36:37], s[28:29], s[0:1]
	s_lshl_b32 s34, s33, 7
	v_mov_b32_e32 v5, s37
	v_or_b32_e32 v4, s36, v158
	v_mov_b32_e32 v13, s37
	v_or_b32_e32 v12, s36, v110
	s_mul_i32 s29, s33, 0x404
	v_lshl_add_u64 v[2:3], v[106:107], 0, s[34:35]
	v_lshlrev_b64 v[116:117], 11, v[4:5]
	v_lshlrev_b64 v[114:115], 11, v[12:13]
	v_mov_b32_e32 v0, s29
	v_lshl_add_u64 v[8:9], v[2:3], 0, v[116:117]
	v_lshl_add_u64 v[2:3], v[2:3], 0, v[114:115]
	ds_read_b32 v138, v0 offset:1024
	global_load_dwordx4 v[4:7], v[8:9], off
	s_nop 0
	global_load_dwordx4 v[8:11], v[8:9], off offset:64
	s_nop 0
	global_load_dwordx4 v[12:15], v[2:3], off
	global_load_dwordx4 v[16:19], v[2:3], off offset:64
	v_lshl_add_u64 v[2:3], s[18:19], 0, v[104:105]
	v_lshlrev_b64 v[2:3], 11, v[2:3]
	s_lshl_b32 s17, s33, 6
	v_lshl_add_u64 v[2:3], s[68:69], 0, v[2:3]
	v_lshl_add_u64 v[2:3], v[2:3], 0, s[34:35]
	v_add_u32_e32 v0, s17, v104
	s_mov_b32 s18, 0x24800
	v_sub_u32_e64 v24, s39, 8 clamp
	v_lshl_add_u64 v[118:119], v[2:3], 0, v[112:113]
	v_mad_i64_i32 v[2:3], s[18:19], v0, s18, v[152:153]
	s_lshl_b64 s[12:13], s[12:13], 14
	v_lshl_add_u64 v[2:3], v[2:3], 0, s[12:13]
	v_lshlrev_b32_e32 v0, 17, v24
	v_lshl_add_u64 v[120:121], v[2:3], 0, v[112:113]
	v_lshl_add_u64 v[2:3], v[118:119], 0, v[0:1]
	global_load_dwordx4 v[20:23], v[2:3], off
	v_lshlrev_b32_e32 v2, 7, v24
	v_mov_b32_e32 v3, v1
	v_lshl_add_u64 v[2:3], v[120:121], 0, v[2:3]
	v_readfirstlane_b32 s28, v24
	global_load_dwordx4 v[24:27], v[2:3], off
	v_or_b32_e32 v0, 0x20000, v0
	s_max_i32 s40, s16, 8
	s_or_b32 s33, s39, 3
	s_add_i32 s36, s40, -8
	v_mov_b32_e32 v142, 0xf149f2ca
	v_mov_b32_e32 v141, 0
	s_mov_b32 s34, s38
	v_mov_b32_e32 v139, 0
	v_mov_b32_e32 v140, 0xf149f2ca
	s_waitcnt vmcnt(1)
	ds_write_b128 v103, v[20:23] offset:16512
	s_waitcnt vmcnt(0)
	ds_write_b128 v103, v[24:27] offset:34944
	v_lshl_add_u64 v[20:21], v[118:119], 0, v[0:1]
	global_load_dwordx4 v[20:23], v[20:21], off
	s_nop 0
	global_load_dwordx4 v[24:27], v[2:3], off offset:128
	v_mov_b32_e32 v2, v1
	v_mov_b32_e32 v3, v1
	v_mov_b32_e32 v0, v1
	v_mov_b64_e32 v[54:55], v[2:3]
	v_mov_b64_e32 v[30:31], v[2:3]
	v_mov_b64_e32 v[62:63], v[2:3]
	v_mov_b64_e32 v[42:43], v[2:3]
	v_mov_b64_e32 v[58:59], v[2:3]
	v_mov_b64_e32 v[46:47], v[2:3]
	v_mov_b64_e32 v[66:67], v[2:3]
	v_mov_b64_e32 v[50:51], v[2:3]
	v_mov_b64_e32 v[52:53], v[0:1]
	v_mov_b64_e32 v[28:29], v[0:1]
	v_mov_b64_e32 v[60:61], v[0:1]
	v_mov_b64_e32 v[40:41], v[0:1]
	v_mov_b64_e32 v[56:57], v[0:1]
	v_mov_b64_e32 v[44:45], v[0:1]
	v_mov_b64_e32 v[64:65], v[0:1]
	v_mov_b64_e32 v[48:49], v[0:1]
	s_waitcnt lgkmcnt(0)
	s_barrier
	s_add_i32 s12, s28, 2
	s_cmp_gt_u32 s12, s33
	s_cbranch_scc0 .LBB0_93
	s_waitcnt vmcnt(1)
	v_mov_b64_e32 v[38:39], v[22:23]
	s_waitcnt vmcnt(0)
	v_mov_b64_e32 v[34:35], v[26:27]
	v_mov_b64_e32 v[32:33], v[24:25]
	v_mov_b64_e32 v[36:37], v[20:21]
	s_branch .LBB0_94

; #define LAS __attribute__((address_space(3)))
; __device__ __forceinline__ void attn_phase(const Args& a, int o, LAS unsigned char* lds) {
;     ...
;                 if (kc < kc_hi) { *(LAS v4u*)(KT + (buf ^ 1) * 64 * KVP + srow * KVP + sseg) = kreg; *(LAS v4u*)(VT + (buf ^ 1) * 64 * KVP + srow * KVP + sseg) = vreg; }
.LBB0_105:
	s_lshl_b32 s18, s37, 6
	s_xor_b32 s18, s18, 64
	s_mulk_i32 s18, 0x90
	v_add_u32_e32 v2, s18, v103
	s_waitcnt vmcnt(2)
	ds_write_b128 v2, v[20:23] offset:16512
	ds_write_b128 v2, v[24:27] offset:34944
